# down-proj phase visits prompt row panels in reverse order (reads most recently written ACT panels first: memory-side cache reuse)
# speedup vs baseline: 1.0003x; 1.0003x over previous
;     __device__ __forceinline__ bool next(int i, Unit& u) const {
;     ...
;         constexpr int NM = 33792 / BM, NFULL = (NM / 8) * 8 * NN;
;         if (L < NFULL) { const int g = L / (8 * NN), idx = L % (8 * NN); u.pm = g * 8 + (idx & 7); u.pn = idx >> 3; }
;         else { constexpr int GS = NM % 8 ? NM % 8 : 8; const int idx = L - NFULL; u.pm = (NM / 8) * 8 + idx % GS; u.pn = idx / GS; }
.LBB0_654:
.LBB0_655:
	s_ashr_i32 s3, s2, 31
	s_lshr_b32 s3, s3, 27
	s_add_i32 s3, s2, s3
	s_ashr_i32 s6, s3, 5
	s_andn2_b32 s3, s3, 31
	s_sub_i32 s2, s2, s3
	s_lshl_b32 s3, s6, 3
	s_and_b32 s6, s2, 7
	s_or_b32 s68, s3, s6
	s_sub_i32 s68, 0x7f, s68
	s_ashr_i32 s67, s2, 3

;     __device__ __forceinline__ bool next(int i, Unit& u) const {
;     ...
;         constexpr int NM = 33792 / BM, NFULL = (NM / 8) * 8 * NN;
;         if (L < NFULL) { const int g = L / (8 * NN), idx = L % (8 * NN); u.pm = g * 8 + (idx & 7); u.pn = idx >> 3; }
;         else { constexpr int GS = NM % 8 ? NM % 8 : 8; const int idx = L - NFULL; u.pm = (NM / 8) * 8 + idx % GS; u.pn = idx / GS; }
.LBB0_664:
	s_andn2_b64 vcc, exec, s[6:7]
	s_cbranch_vccnz .LBB0_666
	s_ashr_i32 s6, s18, 31
	s_lshr_b32 s6, s6, 27
	s_add_i32 s6, s18, s6
	s_ashr_i32 s7, s6, 5
	s_andn2_b32 s6, s6, 31
	s_sub_i32 s6, s18, s6
	s_lshl_b32 s7, s7, 3
	s_and_b32 s18, s6, 7
	s_or_b32 s63, s7, s18
	s_sub_i32 s63, 0x7f, s63
	s_ashr_i32 s66, s6, 3

;     __device__ __forceinline__ bool next(int i, Unit& u) const {
;     ...
;         constexpr int NM = 33792 / BM, NFULL = (NM / 8) * 8 * NN;
;         if (L < NFULL) { const int g = L / (8 * NN), idx = L % (8 * NN); u.pm = g * 8 + (idx & 7); u.pn = idx >> 3; }
;         else { constexpr int GS = NM % 8 ? NM % 8 : 8; const int idx = L - NFULL; u.pm = (NM / 8) * 8 + idx % GS; u.pn = idx / GS; }
.LBB0_1277:
.LBB0_1278:
	s_ashr_i32 s3, s2, 31
	s_lshr_b32 s3, s3, 27
	s_add_i32 s3, s2, s3
	s_ashr_i32 s6, s3, 5
	s_andn2_b32 s3, s3, 31
	s_sub_i32 s2, s2, s3
	s_lshl_b32 s3, s6, 3
	s_and_b32 s6, s2, 7
	s_or_b32 s58, s3, s6
	s_sub_i32 s58, 0x7f, s58
	s_ashr_i32 s57, s2, 3

;     __device__ __forceinline__ bool next(int i, Unit& u) const {
;     ...
;         constexpr int NM = 33792 / BM, NFULL = (NM / 8) * 8 * NN;
;         if (L < NFULL) { const int g = L / (8 * NN), idx = L % (8 * NN); u.pm = g * 8 + (idx & 7); u.pn = idx >> 3; }
;         else { constexpr int GS = NM % 8 ? NM % 8 : 8; const int idx = L - NFULL; u.pm = (NM / 8) * 8 + idx % GS; u.pn = idx / GS; }
.LBB0_1287:
	s_andn2_b64 vcc, exec, s[6:7]
	s_cbranch_vccnz .LBB0_1289
	s_ashr_i32 s6, s16, 31
	s_lshr_b32 s6, s6, 27
	s_add_i32 s6, s16, s6
	s_ashr_i32 s7, s6, 5
	s_andn2_b32 s6, s6, 31
	s_sub_i32 s6, s16, s6
	s_lshl_b32 s7, s7, 3
	s_and_b32 s16, s6, 7
	s_or_b32 s54, s7, s16
	s_sub_i32 s54, 0x7f, s54
	s_ashr_i32 s55, s6, 3
